# v12 plus s_sleep in the stagger spin loop
# baseline (speedup 1.0000x reference)
;     __host__ __device__ bool next(int i, Unit& u) const {
;         u.kt0 = 0; u.nkt = nkt; u.sliced = 0; u.ha = -1; u.hb = -1;
;         if (mode == 0 || i < rounds) { const long L = (long)i * G + c; if (L >= nwg) return false; tile((int)L, u); return true; }
;         if (i > rounds || c >= left * mode) return false;
;         int t, piece;
;         if ((left & 7) == 0) { const int q = c >> 3, x = c & 7; t = x + 8 * (q / mode); piece = q % mode; } else { t = c / mode; piece = c % mode; }
;         tile(rounds * G + t, u); u.ha = piece & 1; u.hb = (mode == 4) ? (piece >> 1) : -1; return true;
.Lstag_spin:
	s_sleep 4
	s_memrealtime s[100:101]
	s_waitcnt lgkmcnt(0)
	s_sub_u32 s98, s100, s99
	s_cmp_lt_i32 s98, 0
	s_cbranch_scc1 .Lstag_spin
